# GEMM K-loops: LDS-DMA loads use SGPR base + 32-bit VGPR offset (no per-load 64-bit VALU address adds)
# baseline (speedup 1.0000x reference)
.LBB0_348:
	s_add_i32 s12, s12, s11
	s_add_u32 s11, s44, s12
	s_addc_u32 s12, s45, 0
	s_add_u32 s10, s42, s10
	s_addc_u32 s13, s43, 0
	s_add_u32 s10, s10, 0x100
	s_addc_u32 s13, s13, 0
	s_add_i32 s14, 0, 0x10000
	s_and_b64 s[0:1], exec, s[0:1]
	v_add_u32_e32 v155, s14, v152
	s_cselect_b32 s1, s6, s13
	s_cselect_b32 s0, s7, s10
	s_add_i32 s13, 0, 0x14000
	ds_read_b128 v[140:143], v155
	ds_read_b128 v[148:151], v155 offset:1024
	ds_read_b128 v[156:159], v155 offset:2048
	ds_read_b128 v[160:163], v155 offset:3072
	v_add_u32_e32 v155, s13, v152
	ds_read_b128 v[164:167], v155
	ds_read_b128 v[168:171], v155 offset:1024
	ds_read_b128 v[172:175], v155 offset:2048
	ds_read_b128 v[176:179], v155 offset:3072
	s_add_u32 s10, s11, 0x140080
	s_addc_u32 s11, s12, 0
	s_add_i32 m0, s53, 0xc000
	ds_read_b128 v[180:183], v154
	ds_read_b128 v[184:187], v154 offset:1024
	ds_read_b128 v[188:191], v154 offset:2048
	ds_read_b128 v[192:195], v154 offset:3072
	ds_read_b128 v[196:199], v154 offset:4096
	ds_read_b128 v[200:203], v154 offset:5120
	ds_read_b128 v[204:207], v154 offset:6144
	ds_read_b128 v[208:211], v154 offset:7168
	global_load_lds_dwordx4 v146, s[10:11]
	s_add_i32 m0, s53, 0xe000
	s_nop 0
	global_load_lds_dwordx4 v136, s[10:11]
	s_waitcnt vmcnt(8)
	s_waitcnt lgkmcnt(0)
	s_barrier
	s_setprio 1
	s_waitcnt lgkmcnt(0)
	v_mfma_f32_16x16x32_bf16 v[122:125], v[140:143], v[180:183], v[122:125]
	v_mfma_f32_16x16x32_bf16 v[114:117], v[156:159], v[180:183], v[114:117]
	v_mfma_f32_16x16x32_bf16 v[102:105], v[140:143], v[188:191], v[102:105]
	v_mfma_f32_16x16x32_bf16 v[78:81], v[156:159], v[188:191], v[78:81]
	v_mfma_f32_16x16x32_bf16 v[70:73], v[140:143], v[196:199], v[70:73]
	v_mfma_f32_16x16x32_bf16 v[50:53], v[156:159], v[196:199], v[50:53]
	v_mfma_f32_16x16x32_bf16 v[42:45], v[140:143], v[204:207], v[42:45]
	v_mfma_f32_16x16x32_bf16 v[26:29], v[156:159], v[204:207], v[26:29]
	v_mfma_f32_16x16x32_bf16 v[122:125], v[148:151], v[184:187], v[122:125]
	v_mfma_f32_16x16x32_bf16 v[114:117], v[160:163], v[184:187], v[114:117]
	v_mfma_f32_16x16x32_bf16 v[102:105], v[148:151], v[192:195], v[102:105]
	v_mfma_f32_16x16x32_bf16 v[78:81], v[160:163], v[192:195], v[78:81]
	v_mfma_f32_16x16x32_bf16 v[70:73], v[148:151], v[200:203], v[70:73]
	v_mfma_f32_16x16x32_bf16 v[50:53], v[160:163], v[200:203], v[50:53]
	v_mfma_f32_16x16x32_bf16 v[42:45], v[148:151], v[208:211], v[42:45]
	v_mfma_f32_16x16x32_bf16 v[26:29], v[160:163], v[208:211], v[26:29]
	s_setprio 0
	s_setprio 1
	v_mfma_f32_16x16x32_bf16 v[126:129], v[164:167], v[180:183], v[126:129]
	v_mfma_f32_16x16x32_bf16 v[130:133], v[172:175], v[180:183], v[130:133]
	v_mfma_f32_16x16x32_bf16 v[110:113], v[164:167], v[188:191], v[110:113]
	v_mfma_f32_16x16x32_bf16 v[118:121], v[172:175], v[188:191], v[118:121]
	v_mfma_f32_16x16x32_bf16 v[86:89], v[164:167], v[196:199], v[86:89]
	v_mfma_f32_16x16x32_bf16 v[90:93], v[172:175], v[196:199], v[90:93]
	v_mfma_f32_16x16x32_bf16 v[58:61], v[164:167], v[204:207], v[58:61]
	v_mfma_f32_16x16x32_bf16 v[94:97], v[172:175], v[204:207], v[94:97]
	v_mfma_f32_16x16x32_bf16 v[126:129], v[168:171], v[184:187], v[126:129]
	v_mfma_f32_16x16x32_bf16 v[130:133], v[176:179], v[184:187], v[130:133]
	v_mfma_f32_16x16x32_bf16 v[110:113], v[168:171], v[192:195], v[110:113]
	v_mfma_f32_16x16x32_bf16 v[118:121], v[176:179], v[192:195], v[118:121]
	v_mfma_f32_16x16x32_bf16 v[86:89], v[168:171], v[200:203], v[86:89]
	v_mfma_f32_16x16x32_bf16 v[90:93], v[176:179], v[200:203], v[90:93]
	v_mfma_f32_16x16x32_bf16 v[58:61], v[168:171], v[208:211], v[58:61]
	v_mfma_f32_16x16x32_bf16 v[94:97], v[176:179], v[208:211], v[94:97]
	s_setprio 0
	s_barrier
	s_add_i32 s10, s14, s52
	s_mov_b32 m0, s10
	ds_read_b128 v[180:183], v154 offset:16384
	ds_read_b128 v[184:187], v154 offset:17408
	ds_read_b128 v[188:191], v154 offset:18432
	ds_read_b128 v[192:195], v154 offset:19456
	ds_read_b128 v[196:199], v154 offset:20480
	ds_read_b128 v[200:203], v154 offset:21504
	ds_read_b128 v[204:207], v154 offset:22528
	ds_read_b128 v[208:211], v154 offset:23552
	global_load_lds_dwordx4 v138, s[0:1]
	s_add_i32 m0, s10, 0x2000
	s_add_u32 s10, s0, 0x80000
	s_addc_u32 s11, s1, 0
	s_add_i32 s12, s13, s52
	global_load_lds_dwordx4 v134, s[0:1]
	s_mov_b32 m0, s12
	s_nop 0
	global_load_lds_dwordx4 v138, s[10:11]
	s_add_i32 m0, s12, 0x2000
	s_nop 0
	global_load_lds_dwordx4 v134, s[10:11]
	s_mov_b32 m0, s53
	s_nop 0
	global_load_lds_dwordx4 v146, s[46:47]
	s_mov_b32 m0, s54
	s_nop 0
	global_load_lds_dwordx4 v136, s[46:47]
	s_waitcnt vmcnt(8)
	s_waitcnt lgkmcnt(0)
	s_barrier
	s_setprio 1
	s_waitcnt lgkmcnt(0)
	v_mfma_f32_16x16x32_bf16 v[82:85], v[140:143], v[180:183], v[82:85]
	v_mfma_f32_16x16x32_bf16 v[62:65], v[156:159], v[180:183], v[62:65]
	v_mfma_f32_16x16x32_bf16 v[54:57], v[140:143], v[188:191], v[54:57]
	v_mfma_f32_16x16x32_bf16 v[34:37], v[156:159], v[188:191], v[34:37]
	v_mfma_f32_16x16x32_bf16 v[30:33], v[140:143], v[196:199], v[30:33]
	v_mfma_f32_16x16x32_bf16 v[14:17], v[156:159], v[196:199], v[14:17]
	v_mfma_f32_16x16x32_bf16 v[10:13], v[140:143], v[204:207], v[10:13]
	v_mfma_f32_16x16x32_bf16 v[6:9], v[156:159], v[204:207], v[6:9]
	v_mfma_f32_16x16x32_bf16 v[82:85], v[148:151], v[184:187], v[82:85]
	v_mfma_f32_16x16x32_bf16 v[62:65], v[160:163], v[184:187], v[62:65]
	v_mfma_f32_16x16x32_bf16 v[54:57], v[148:151], v[192:195], v[54:57]
	v_mfma_f32_16x16x32_bf16 v[34:37], v[160:163], v[192:195], v[34:37]
	v_mfma_f32_16x16x32_bf16 v[30:33], v[148:151], v[200:203], v[30:33]
	v_mfma_f32_16x16x32_bf16 v[14:17], v[160:163], v[200:203], v[14:17]
	v_mfma_f32_16x16x32_bf16 v[10:13], v[148:151], v[208:211], v[10:13]
	v_mfma_f32_16x16x32_bf16 v[6:9], v[160:163], v[208:211], v[6:9]
	s_setprio 0
	s_setprio 1
	v_mfma_f32_16x16x32_bf16 v[98:101], v[164:167], v[180:183], v[98:101]
	v_mfma_f32_16x16x32_bf16 v[106:109], v[172:175], v[180:183], v[106:109]
	v_mfma_f32_16x16x32_bf16 v[66:69], v[164:167], v[188:191], v[66:69]
	v_mfma_f32_16x16x32_bf16 v[74:77], v[172:175], v[188:191], v[74:77]
	v_mfma_f32_16x16x32_bf16 v[38:41], v[164:167], v[196:199], v[38:41]
	v_mfma_f32_16x16x32_bf16 v[46:49], v[172:175], v[196:199], v[46:49]
	v_mfma_f32_16x16x32_bf16 v[18:21], v[164:167], v[204:207], v[18:21]
	v_mfma_f32_16x16x32_bf16 v[22:25], v[172:175], v[204:207], v[22:25]
	v_mfma_f32_16x16x32_bf16 v[98:101], v[168:171], v[184:187], v[98:101]
	v_mfma_f32_16x16x32_bf16 v[106:109], v[176:179], v[184:187], v[106:109]
	v_mfma_f32_16x16x32_bf16 v[66:69], v[168:171], v[192:195], v[66:69]
	v_mfma_f32_16x16x32_bf16 v[74:77], v[176:179], v[192:195], v[74:77]
	v_mfma_f32_16x16x32_bf16 v[38:41], v[168:171], v[200:203], v[38:41]
	v_mfma_f32_16x16x32_bf16 v[46:49], v[176:179], v[200:203], v[46:49]
	v_mfma_f32_16x16x32_bf16 v[18:21], v[168:171], v[208:211], v[18:21]
	v_mfma_f32_16x16x32_bf16 v[22:25], v[176:179], v[208:211], v[22:25]
	s_setprio 0
	s_barrier
	s_add_i32 s12, 0, 0x18000
	v_add_u32_e32 v155, s12, v152
	s_add_i32 s13, 0, 0x1c000
	ds_read_b128 v[140:143], v155
	ds_read_b128 v[148:151], v155 offset:1024
	ds_read_b128 v[156:159], v155 offset:2048
	ds_read_b128 v[160:163], v155 offset:3072
	v_add_u32_e32 v155, s13, v152
	ds_read_b128 v[164:167], v155
	ds_read_b128 v[168:171], v155 offset:1024
	ds_read_b128 v[172:175], v155 offset:2048
	ds_read_b128 v[176:179], v155 offset:3072
	s_add_u32 s10, s46, 0x140000
	s_addc_u32 s11, s47, 0
	s_mov_b32 m0, s55
	ds_read_b128 v[180:183], v154 offset:32768
	ds_read_b128 v[184:187], v154 offset:33792
	ds_read_b128 v[188:191], v154 offset:34816
	ds_read_b128 v[192:195], v154 offset:35840
	ds_read_b128 v[196:199], v154 offset:36864
	ds_read_b128 v[200:203], v154 offset:37888
	ds_read_b128 v[204:207], v154 offset:38912
	ds_read_b128 v[208:211], v154 offset:39936
	global_load_lds_dwordx4 v146, s[10:11]
	s_mov_b32 m0, s56
	s_nop 0
	global_load_lds_dwordx4 v136, s[10:11]
	s_waitcnt vmcnt(8)
	s_waitcnt lgkmcnt(0)
	s_barrier
	s_setprio 1
	s_waitcnt lgkmcnt(0)
	v_mfma_f32_16x16x32_bf16 v[122:125], v[140:143], v[180:183], v[122:125]
	v_mfma_f32_16x16x32_bf16 v[114:117], v[156:159], v[180:183], v[114:117]
	v_mfma_f32_16x16x32_bf16 v[102:105], v[140:143], v[188:191], v[102:105]
	v_mfma_f32_16x16x32_bf16 v[78:81], v[156:159], v[188:191], v[78:81]
	v_mfma_f32_16x16x32_bf16 v[70:73], v[140:143], v[196:199], v[70:73]
	v_mfma_f32_16x16x32_bf16 v[50:53], v[156:159], v[196:199], v[50:53]
	v_mfma_f32_16x16x32_bf16 v[42:45], v[140:143], v[204:207], v[42:45]
	v_mfma_f32_16x16x32_bf16 v[26:29], v[156:159], v[204:207], v[26:29]
	v_mfma_f32_16x16x32_bf16 v[122:125], v[148:151], v[184:187], v[122:125]
	v_mfma_f32_16x16x32_bf16 v[114:117], v[160:163], v[184:187], v[114:117]
	v_mfma_f32_16x16x32_bf16 v[102:105], v[148:151], v[192:195], v[102:105]
	v_mfma_f32_16x16x32_bf16 v[78:81], v[160:163], v[192:195], v[78:81]
	v_mfma_f32_16x16x32_bf16 v[70:73], v[148:151], v[200:203], v[70:73]
	v_mfma_f32_16x16x32_bf16 v[50:53], v[160:163], v[200:203], v[50:53]
	v_mfma_f32_16x16x32_bf16 v[42:45], v[148:151], v[208:211], v[42:45]
	v_mfma_f32_16x16x32_bf16 v[26:29], v[160:163], v[208:211], v[26:29]
	s_setprio 0
	s_setprio 1
	v_mfma_f32_16x16x32_bf16 v[126:129], v[164:167], v[180:183], v[126:129]
	v_mfma_f32_16x16x32_bf16 v[130:133], v[172:175], v[180:183], v[130:133]
	v_mfma_f32_16x16x32_bf16 v[110:113], v[164:167], v[188:191], v[110:113]
	v_mfma_f32_16x16x32_bf16 v[118:121], v[172:175], v[188:191], v[118:121]
	v_mfma_f32_16x16x32_bf16 v[86:89], v[164:167], v[196:199], v[86:89]
	v_mfma_f32_16x16x32_bf16 v[90:93], v[172:175], v[196:199], v[90:93]
	v_mfma_f32_16x16x32_bf16 v[58:61], v[164:167], v[204:207], v[58:61]
	v_mfma_f32_16x16x32_bf16 v[94:97], v[172:175], v[204:207], v[94:97]
	v_mfma_f32_16x16x32_bf16 v[126:129], v[168:171], v[184:187], v[126:129]
	v_mfma_f32_16x16x32_bf16 v[130:133], v[176:179], v[184:187], v[130:133]
	v_mfma_f32_16x16x32_bf16 v[110:113], v[168:171], v[192:195], v[110:113]
	v_mfma_f32_16x16x32_bf16 v[118:121], v[176:179], v[192:195], v[118:121]
	v_mfma_f32_16x16x32_bf16 v[86:89], v[168:171], v[200:203], v[86:89]
	v_mfma_f32_16x16x32_bf16 v[90:93], v[176:179], v[200:203], v[90:93]
	v_mfma_f32_16x16x32_bf16 v[58:61], v[168:171], v[208:211], v[58:61]
	v_mfma_f32_16x16x32_bf16 v[94:97], v[176:179], v[208:211], v[94:97]
	s_setprio 0
	s_barrier
	s_mov_b64 s[14:15], 0x80
	s_add_i32 s10, s12, s52
	s_add_u32 s62, s0, 0x80
	s_addc_u32 s63, s1, 0
	s_mov_b32 m0, s10
	ds_read_b128 v[180:183], v154 offset:49152
	ds_read_b128 v[184:187], v154 offset:50176
	ds_read_b128 v[188:191], v154 offset:51200
	ds_read_b128 v[192:195], v154 offset:52224
	ds_read_b128 v[196:199], v154 offset:53248
	ds_read_b128 v[200:203], v154 offset:54272
	ds_read_b128 v[204:207], v154 offset:55296
	ds_read_b128 v[208:211], v154 offset:56320
	global_load_lds_dwordx4 v138, s[62:63]
	s_add_i32 m0, s10, 0x2000
	s_add_u32 s0, s0, 0x80080
	s_addc_u32 s1, s1, 0
	s_add_i32 s10, s13, s52
	global_load_lds_dwordx4 v134, s[62:63]
	s_mov_b32 m0, s10
	s_nop 0
	global_load_lds_dwordx4 v138, s[0:1]
	s_add_i32 m0, s10, 0x2000
	s_nop 0
	global_load_lds_dwordx4 v134, s[0:1]
	s_add_u32 s64, s46, 0x80
	s_addc_u32 s65, s47, 0
	s_mov_b32 m0, s57
	s_nop 0
	global_load_lds_dwordx4 v146, s[64:65]
	s_mov_b32 m0, s58
	s_nop 0
	global_load_lds_dwordx4 v136, s[64:65]
	s_waitcnt vmcnt(8)
	s_waitcnt lgkmcnt(0)
	s_barrier
	s_setprio 1
	s_waitcnt lgkmcnt(0)
	v_mfma_f32_16x16x32_bf16 v[82:85], v[140:143], v[180:183], v[82:85]
	v_mfma_f32_16x16x32_bf16 v[62:65], v[156:159], v[180:183], v[62:65]
	v_mfma_f32_16x16x32_bf16 v[54:57], v[140:143], v[188:191], v[54:57]
	v_mfma_f32_16x16x32_bf16 v[34:37], v[156:159], v[188:191], v[34:37]
	v_mfma_f32_16x16x32_bf16 v[30:33], v[140:143], v[196:199], v[30:33]
	v_mfma_f32_16x16x32_bf16 v[14:17], v[156:159], v[196:199], v[14:17]
	v_mfma_f32_16x16x32_bf16 v[10:13], v[140:143], v[204:207], v[10:13]
	v_mfma_f32_16x16x32_bf16 v[6:9], v[156:159], v[204:207], v[6:9]
	v_mfma_f32_16x16x32_bf16 v[82:85], v[148:151], v[184:187], v[82:85]
	v_mfma_f32_16x16x32_bf16 v[62:65], v[160:163], v[184:187], v[62:65]
	v_mfma_f32_16x16x32_bf16 v[54:57], v[148:151], v[192:195], v[54:57]
	v_mfma_f32_16x16x32_bf16 v[34:37], v[160:163], v[192:195], v[34:37]
	v_mfma_f32_16x16x32_bf16 v[30:33], v[148:151], v[200:203], v[30:33]
	v_mfma_f32_16x16x32_bf16 v[14:17], v[160:163], v[200:203], v[14:17]
	v_mfma_f32_16x16x32_bf16 v[10:13], v[148:151], v[208:211], v[10:13]
	v_mfma_f32_16x16x32_bf16 v[6:9], v[160:163], v[208:211], v[6:9]
	s_setprio 0
	s_setprio 1
	v_mfma_f32_16x16x32_bf16 v[98:101], v[164:167], v[180:183], v[98:101]
	v_mfma_f32_16x16x32_bf16 v[106:109], v[172:175], v[180:183], v[106:109]
	v_mfma_f32_16x16x32_bf16 v[66:69], v[164:167], v[188:191], v[66:69]
	v_mfma_f32_16x16x32_bf16 v[74:77], v[172:175], v[188:191], v[74:77]
	v_mfma_f32_16x16x32_bf16 v[38:41], v[164:167], v[196:199], v[38:41]
	v_mfma_f32_16x16x32_bf16 v[46:49], v[172:175], v[196:199], v[46:49]
	v_mfma_f32_16x16x32_bf16 v[18:21], v[164:167], v[204:207], v[18:21]
	v_mfma_f32_16x16x32_bf16 v[22:25], v[172:175], v[204:207], v[22:25]
	v_mfma_f32_16x16x32_bf16 v[98:101], v[168:171], v[184:187], v[98:101]
	v_mfma_f32_16x16x32_bf16 v[106:109], v[176:179], v[184:187], v[106:109]
	v_mfma_f32_16x16x32_bf16 v[66:69], v[168:171], v[192:195], v[66:69]
	v_mfma_f32_16x16x32_bf16 v[74:77], v[176:179], v[192:195], v[74:77]
	v_mfma_f32_16x16x32_bf16 v[38:41], v[168:171], v[200:203], v[38:41]
	v_mfma_f32_16x16x32_bf16 v[46:49], v[176:179], v[200:203], v[46:49]
	v_mfma_f32_16x16x32_bf16 v[18:21], v[168:171], v[208:211], v[18:21]
	v_mfma_f32_16x16x32_bf16 v[22:25], v[176:179], v[208:211], v[22:25]
	s_setprio 0
	s_barrier
	s_cmp_gt_u32 s8, 29
	s_cbranch_scc1 .LBB0_350
	s_mov_b32 s8, s9
	s_branch .LBB0_346

.LBB0_625:
	s_add_u32 s13, s0, 0xfffc0080
	s_addc_u32 s14, s1, -1
	s_add_i32 s15, 0, 0x10000
	s_cmp_eq_u32 s12, 12
	s_cselect_b32 s39, s6, s14
	s_cselect_b32 s38, s7, s13
	v_add_u32_e32 v138, s15, v151
	s_cselect_b32 s35, s8, s11
	s_cselect_b32 s34, s9, s10
	s_add_i32 s13, 0, 0x14000
	ds_read_b128 v[164:167], v138
	ds_read_b128 v[168:171], v138 offset:1024
	ds_read_b128 v[172:175], v138 offset:2048
	ds_read_b128 v[176:179], v138 offset:3072
	v_add_u32_e32 v138, s13, v151
	ds_read_b128 v[180:183], v138
	ds_read_b128 v[184:187], v138 offset:1024
	ds_read_b128 v[188:191], v138 offset:2048
	ds_read_b128 v[192:195], v138 offset:3072
	s_add_i32 m0, s59, 0xc000
	ds_read_b128 v[196:199], v162
	ds_read_b128 v[200:203], v162 offset:1024
	ds_read_b128 v[204:207], v162 offset:2048
	ds_read_b128 v[208:211], v162 offset:3072
	ds_read_b128 v[212:215], v162 offset:4096
	ds_read_b128 v[216:219], v162 offset:5120
	ds_read_b128 v[236:239], v162 offset:6144
	ds_read_b128 v[240:243], v162 offset:7168
	global_load_lds_dwordx4 v154, s[0:1]
	s_add_i32 m0, s59, 0xe000
	s_nop 0
	global_load_lds_dwordx4 v156, s[0:1]
	s_waitcnt vmcnt(8)
	s_waitcnt lgkmcnt(0)
	s_barrier
	s_setprio 1
	s_waitcnt lgkmcnt(0)
	v_mfma_f32_16x16x32_bf16 v[130:133], v[164:167], v[196:199], v[130:133]
	v_mfma_f32_16x16x32_bf16 v[126:129], v[172:175], v[196:199], v[126:129]
	v_mfma_f32_16x16x32_bf16 v[114:117], v[164:167], v[204:207], v[114:117]
	v_mfma_f32_16x16x32_bf16 v[110:113], v[172:175], v[204:207], v[110:113]
	v_mfma_f32_16x16x32_bf16 v[98:101], v[164:167], v[212:215], v[98:101]
	v_mfma_f32_16x16x32_bf16 v[94:97], v[172:175], v[212:215], v[94:97]
	v_mfma_f32_16x16x32_bf16 v[82:85], v[164:167], v[236:239], v[82:85]
	v_mfma_f32_16x16x32_bf16 v[78:81], v[172:175], v[236:239], v[78:81]
	v_mfma_f32_16x16x32_bf16 v[130:133], v[168:171], v[200:203], v[130:133]
	v_mfma_f32_16x16x32_bf16 v[126:129], v[176:179], v[200:203], v[126:129]
	v_mfma_f32_16x16x32_bf16 v[114:117], v[168:171], v[208:211], v[114:117]
	v_mfma_f32_16x16x32_bf16 v[110:113], v[176:179], v[208:211], v[110:113]
	v_mfma_f32_16x16x32_bf16 v[98:101], v[168:171], v[216:219], v[98:101]
	v_mfma_f32_16x16x32_bf16 v[94:97], v[176:179], v[216:219], v[94:97]
	v_mfma_f32_16x16x32_bf16 v[82:85], v[168:171], v[240:243], v[82:85]
	v_mfma_f32_16x16x32_bf16 v[78:81], v[176:179], v[240:243], v[78:81]
	s_setprio 0
	s_setprio 1
	v_mfma_f32_16x16x32_bf16 v[122:125], v[180:183], v[196:199], v[122:125]
	v_mfma_f32_16x16x32_bf16 v[118:121], v[188:191], v[196:199], v[118:121]
	v_mfma_f32_16x16x32_bf16 v[106:109], v[180:183], v[204:207], v[106:109]
	v_mfma_f32_16x16x32_bf16 v[102:105], v[188:191], v[204:207], v[102:105]
	v_mfma_f32_16x16x32_bf16 v[90:93], v[180:183], v[212:215], v[90:93]
	v_mfma_f32_16x16x32_bf16 v[86:89], v[188:191], v[212:215], v[86:89]
	v_mfma_f32_16x16x32_bf16 v[74:77], v[180:183], v[236:239], v[74:77]
	v_mfma_f32_16x16x32_bf16 v[70:73], v[188:191], v[236:239], v[70:73]
	v_mfma_f32_16x16x32_bf16 v[122:125], v[184:187], v[200:203], v[122:125]
	v_mfma_f32_16x16x32_bf16 v[118:121], v[192:195], v[200:203], v[118:121]
	v_mfma_f32_16x16x32_bf16 v[106:109], v[184:187], v[208:211], v[106:109]
	v_mfma_f32_16x16x32_bf16 v[102:105], v[192:195], v[208:211], v[102:105]
	v_mfma_f32_16x16x32_bf16 v[90:93], v[184:187], v[216:219], v[90:93]
	v_mfma_f32_16x16x32_bf16 v[86:89], v[192:195], v[216:219], v[86:89]
	v_mfma_f32_16x16x32_bf16 v[74:77], v[184:187], v[240:243], v[74:77]
	v_mfma_f32_16x16x32_bf16 v[70:73], v[192:195], v[240:243], v[70:73]
	s_setprio 0
	s_barrier
	s_add_i32 s14, s15, s56
	s_mov_b32 m0, s14
	ds_read_b128 v[196:199], v162 offset:16384
	ds_read_b128 v[200:203], v162 offset:17408
	ds_read_b128 v[204:207], v162 offset:18432
	ds_read_b128 v[208:211], v162 offset:19456
	ds_read_b128 v[212:215], v162 offset:20480
	ds_read_b128 v[216:219], v162 offset:21504
	ds_read_b128 v[236:239], v162 offset:22528
	ds_read_b128 v[240:243], v162 offset:23552
	global_load_lds_dwordx4 v146, s[34:35]
	s_add_i32 m0, s14, 0x2000
	s_add_u32 s14, s34, 0x40000
	s_addc_u32 s15, s35, 0
	s_add_i32 s13, s13, s56
	global_load_lds_dwordx4 v134, s[34:35]
	s_mov_b32 m0, s13
	s_nop 0
	global_load_lds_dwordx4 v146, s[14:15]
	s_add_i32 m0, s13, 0x2000
	s_nop 0
	global_load_lds_dwordx4 v134, s[14:15]
	s_mov_b32 m0, s59
	s_nop 0
	global_load_lds_dwordx4 v148, s[38:39]
	s_mov_b32 m0, s60
	s_nop 0
	global_load_lds_dwordx4 v136, s[38:39]
	s_waitcnt vmcnt(8)
	s_waitcnt lgkmcnt(0)
	s_barrier
	s_setprio 1
	s_waitcnt lgkmcnt(0)
	v_mfma_f32_16x16x32_bf16 v[66:69], v[164:167], v[196:199], v[66:69]
	v_mfma_f32_16x16x32_bf16 v[62:65], v[172:175], v[196:199], v[62:65]
	v_mfma_f32_16x16x32_bf16 v[50:53], v[164:167], v[204:207], v[50:53]
	v_mfma_f32_16x16x32_bf16 v[46:49], v[172:175], v[204:207], v[46:49]
	v_mfma_f32_16x16x32_bf16 v[34:37], v[164:167], v[212:215], v[34:37]
	v_mfma_f32_16x16x32_bf16 v[30:33], v[172:175], v[212:215], v[30:33]
	v_mfma_f32_16x16x32_bf16 v[18:21], v[164:167], v[236:239], v[18:21]
	v_mfma_f32_16x16x32_bf16 v[14:17], v[172:175], v[236:239], v[14:17]
	v_mfma_f32_16x16x32_bf16 v[66:69], v[168:171], v[200:203], v[66:69]
	v_mfma_f32_16x16x32_bf16 v[62:65], v[176:179], v[200:203], v[62:65]
	v_mfma_f32_16x16x32_bf16 v[50:53], v[168:171], v[208:211], v[50:53]
	v_mfma_f32_16x16x32_bf16 v[46:49], v[176:179], v[208:211], v[46:49]
	v_mfma_f32_16x16x32_bf16 v[34:37], v[168:171], v[216:219], v[34:37]
	v_mfma_f32_16x16x32_bf16 v[30:33], v[176:179], v[216:219], v[30:33]
	v_mfma_f32_16x16x32_bf16 v[18:21], v[168:171], v[240:243], v[18:21]
	v_mfma_f32_16x16x32_bf16 v[14:17], v[176:179], v[240:243], v[14:17]
	s_setprio 0
	s_setprio 1
	v_mfma_f32_16x16x32_bf16 v[58:61], v[180:183], v[196:199], v[58:61]
	v_mfma_f32_16x16x32_bf16 v[54:57], v[188:191], v[196:199], v[54:57]
	v_mfma_f32_16x16x32_bf16 v[42:45], v[180:183], v[204:207], v[42:45]
	v_mfma_f32_16x16x32_bf16 v[38:41], v[188:191], v[204:207], v[38:41]
	v_mfma_f32_16x16x32_bf16 v[26:29], v[180:183], v[212:215], v[26:29]
	v_mfma_f32_16x16x32_bf16 v[22:25], v[188:191], v[212:215], v[22:25]
	v_mfma_f32_16x16x32_bf16 v[10:13], v[180:183], v[236:239], v[10:13]
	v_mfma_f32_16x16x32_bf16 v[6:9], v[188:191], v[236:239], v[6:9]
	v_mfma_f32_16x16x32_bf16 v[58:61], v[184:187], v[200:203], v[58:61]
	v_mfma_f32_16x16x32_bf16 v[54:57], v[192:195], v[200:203], v[54:57]
	v_mfma_f32_16x16x32_bf16 v[42:45], v[184:187], v[208:211], v[42:45]
	v_mfma_f32_16x16x32_bf16 v[38:41], v[192:195], v[208:211], v[38:41]
	v_mfma_f32_16x16x32_bf16 v[26:29], v[184:187], v[216:219], v[26:29]
	v_mfma_f32_16x16x32_bf16 v[22:25], v[192:195], v[216:219], v[22:25]
	v_mfma_f32_16x16x32_bf16 v[10:13], v[184:187], v[240:243], v[10:13]
	v_mfma_f32_16x16x32_bf16 v[6:9], v[192:195], v[240:243], v[6:9]
	s_setprio 0
	s_barrier
	s_add_i32 s13, 0, 0x18000
	v_add_u32_e32 v138, s13, v151
	s_add_i32 s16, 0, 0x1c000
	ds_read_b128 v[164:167], v138
	ds_read_b128 v[168:171], v138 offset:1024
	ds_read_b128 v[172:175], v138 offset:2048
	ds_read_b128 v[176:179], v138 offset:3072
	v_add_u32_e32 v138, s16, v151
	ds_read_b128 v[180:183], v138
	ds_read_b128 v[184:187], v138 offset:1024
	ds_read_b128 v[188:191], v138 offset:2048
	ds_read_b128 v[192:195], v138 offset:3072
	s_add_u32 s14, s38, 0x40000
	s_addc_u32 s15, s39, 0
	s_mov_b32 m0, s61
	ds_read_b128 v[196:199], v162 offset:32768
	ds_read_b128 v[200:203], v162 offset:33792
	ds_read_b128 v[204:207], v162 offset:34816
	ds_read_b128 v[208:211], v162 offset:35840
	ds_read_b128 v[212:215], v162 offset:36864
	ds_read_b128 v[216:219], v162 offset:37888
	ds_read_b128 v[236:239], v162 offset:38912
	ds_read_b128 v[240:243], v162 offset:39936
	global_load_lds_dwordx4 v148, s[14:15]
	s_mov_b32 m0, s62
	s_nop 0
	global_load_lds_dwordx4 v136, s[14:15]
	s_waitcnt vmcnt(8)
	s_waitcnt lgkmcnt(0)
	s_barrier
	s_setprio 1
	s_waitcnt lgkmcnt(0)
	v_mfma_f32_16x16x32_bf16 v[130:133], v[164:167], v[196:199], v[130:133]
	v_mfma_f32_16x16x32_bf16 v[126:129], v[172:175], v[196:199], v[126:129]
	v_mfma_f32_16x16x32_bf16 v[114:117], v[164:167], v[204:207], v[114:117]
	v_mfma_f32_16x16x32_bf16 v[110:113], v[172:175], v[204:207], v[110:113]
	v_mfma_f32_16x16x32_bf16 v[98:101], v[164:167], v[212:215], v[98:101]
	v_mfma_f32_16x16x32_bf16 v[94:97], v[172:175], v[212:215], v[94:97]
	v_mfma_f32_16x16x32_bf16 v[82:85], v[164:167], v[236:239], v[82:85]
	v_mfma_f32_16x16x32_bf16 v[78:81], v[172:175], v[236:239], v[78:81]
	v_mfma_f32_16x16x32_bf16 v[130:133], v[168:171], v[200:203], v[130:133]
	v_mfma_f32_16x16x32_bf16 v[126:129], v[176:179], v[200:203], v[126:129]
	v_mfma_f32_16x16x32_bf16 v[114:117], v[168:171], v[208:211], v[114:117]
	v_mfma_f32_16x16x32_bf16 v[110:113], v[176:179], v[208:211], v[110:113]
	v_mfma_f32_16x16x32_bf16 v[98:101], v[168:171], v[216:219], v[98:101]
	v_mfma_f32_16x16x32_bf16 v[94:97], v[176:179], v[216:219], v[94:97]
	v_mfma_f32_16x16x32_bf16 v[82:85], v[168:171], v[240:243], v[82:85]
	v_mfma_f32_16x16x32_bf16 v[78:81], v[176:179], v[240:243], v[78:81]
	s_setprio 0
	s_setprio 1
	v_mfma_f32_16x16x32_bf16 v[122:125], v[180:183], v[196:199], v[122:125]
	v_mfma_f32_16x16x32_bf16 v[118:121], v[188:191], v[196:199], v[118:121]
	v_mfma_f32_16x16x32_bf16 v[106:109], v[180:183], v[204:207], v[106:109]
	v_mfma_f32_16x16x32_bf16 v[102:105], v[188:191], v[204:207], v[102:105]
	v_mfma_f32_16x16x32_bf16 v[90:93], v[180:183], v[212:215], v[90:93]
	v_mfma_f32_16x16x32_bf16 v[86:89], v[188:191], v[212:215], v[86:89]
	v_mfma_f32_16x16x32_bf16 v[74:77], v[180:183], v[236:239], v[74:77]
	v_mfma_f32_16x16x32_bf16 v[70:73], v[188:191], v[236:239], v[70:73]
	v_mfma_f32_16x16x32_bf16 v[122:125], v[184:187], v[200:203], v[122:125]
	v_mfma_f32_16x16x32_bf16 v[118:121], v[192:195], v[200:203], v[118:121]
	v_mfma_f32_16x16x32_bf16 v[106:109], v[184:187], v[208:211], v[106:109]
	v_mfma_f32_16x16x32_bf16 v[102:105], v[192:195], v[208:211], v[102:105]
	v_mfma_f32_16x16x32_bf16 v[90:93], v[184:187], v[216:219], v[90:93]
	v_mfma_f32_16x16x32_bf16 v[86:89], v[192:195], v[216:219], v[86:89]
	v_mfma_f32_16x16x32_bf16 v[74:77], v[184:187], v[240:243], v[74:77]
	v_mfma_f32_16x16x32_bf16 v[70:73], v[192:195], v[240:243], v[70:73]
	s_setprio 0
	s_barrier
	s_add_i32 s13, s13, s56
	s_add_u32 s42, s34, 0x80
	s_addc_u32 s43, s35, 0
	s_mov_b32 m0, s13
	ds_read_b128 v[196:199], v162 offset:49152
	ds_read_b128 v[200:203], v162 offset:50176
	ds_read_b128 v[204:207], v162 offset:51200
	ds_read_b128 v[208:211], v162 offset:52224
	ds_read_b128 v[212:215], v162 offset:53248
	ds_read_b128 v[216:219], v162 offset:54272
	ds_read_b128 v[236:239], v162 offset:55296
	ds_read_b128 v[240:243], v162 offset:56320
	global_load_lds_dwordx4 v146, s[42:43]
	s_add_i32 m0, s13, 0x2000
	s_add_u32 s14, s34, 0x40080
	s_addc_u32 s15, s35, 0
	s_add_i32 s13, s16, s56
	global_load_lds_dwordx4 v134, s[42:43]
	s_mov_b32 m0, s13
	s_nop 0
	global_load_lds_dwordx4 v146, s[14:15]
	s_add_i32 m0, s13, 0x2000
	s_nop 0
	global_load_lds_dwordx4 v134, s[14:15]
	s_add_u32 s50, s38, 0x80
	s_addc_u32 s51, s39, 0
	s_mov_b32 m0, s64
	s_nop 0
	global_load_lds_dwordx4 v148, s[50:51]
	s_mov_b32 m0, s65
	s_nop 0
	global_load_lds_dwordx4 v136, s[50:51]
	s_waitcnt vmcnt(8)
	s_waitcnt lgkmcnt(0)
	s_barrier
	s_setprio 1
	s_waitcnt lgkmcnt(0)
	v_mfma_f32_16x16x32_bf16 v[66:69], v[164:167], v[196:199], v[66:69]
	v_mfma_f32_16x16x32_bf16 v[62:65], v[172:175], v[196:199], v[62:65]
	v_mfma_f32_16x16x32_bf16 v[50:53], v[164:167], v[204:207], v[50:53]
	v_mfma_f32_16x16x32_bf16 v[46:49], v[172:175], v[204:207], v[46:49]
	v_mfma_f32_16x16x32_bf16 v[34:37], v[164:167], v[212:215], v[34:37]
	v_mfma_f32_16x16x32_bf16 v[30:33], v[172:175], v[212:215], v[30:33]
	v_mfma_f32_16x16x32_bf16 v[18:21], v[164:167], v[236:239], v[18:21]
	v_mfma_f32_16x16x32_bf16 v[14:17], v[172:175], v[236:239], v[14:17]
	v_mfma_f32_16x16x32_bf16 v[66:69], v[168:171], v[200:203], v[66:69]
	v_mfma_f32_16x16x32_bf16 v[62:65], v[176:179], v[200:203], v[62:65]
	v_mfma_f32_16x16x32_bf16 v[50:53], v[168:171], v[208:211], v[50:53]
	v_mfma_f32_16x16x32_bf16 v[46:49], v[176:179], v[208:211], v[46:49]
	v_mfma_f32_16x16x32_bf16 v[34:37], v[168:171], v[216:219], v[34:37]
	v_mfma_f32_16x16x32_bf16 v[30:33], v[176:179], v[216:219], v[30:33]
	v_mfma_f32_16x16x32_bf16 v[18:21], v[168:171], v[240:243], v[18:21]
	v_mfma_f32_16x16x32_bf16 v[14:17], v[176:179], v[240:243], v[14:17]
	s_setprio 0
	s_setprio 1
	v_mfma_f32_16x16x32_bf16 v[58:61], v[180:183], v[196:199], v[58:61]
	v_mfma_f32_16x16x32_bf16 v[54:57], v[188:191], v[196:199], v[54:57]
	v_mfma_f32_16x16x32_bf16 v[42:45], v[180:183], v[204:207], v[42:45]
	v_mfma_f32_16x16x32_bf16 v[38:41], v[188:191], v[204:207], v[38:41]
	v_mfma_f32_16x16x32_bf16 v[26:29], v[180:183], v[212:215], v[26:29]
	v_mfma_f32_16x16x32_bf16 v[22:25], v[188:191], v[212:215], v[22:25]
	v_mfma_f32_16x16x32_bf16 v[10:13], v[180:183], v[236:239], v[10:13]
	v_mfma_f32_16x16x32_bf16 v[6:9], v[188:191], v[236:239], v[6:9]
	v_mfma_f32_16x16x32_bf16 v[58:61], v[184:187], v[200:203], v[58:61]
	v_mfma_f32_16x16x32_bf16 v[54:57], v[192:195], v[200:203], v[54:57]
	v_mfma_f32_16x16x32_bf16 v[42:45], v[184:187], v[208:211], v[42:45]
	v_mfma_f32_16x16x32_bf16 v[38:41], v[192:195], v[208:211], v[38:41]
	v_mfma_f32_16x16x32_bf16 v[26:29], v[184:187], v[216:219], v[26:29]
	v_mfma_f32_16x16x32_bf16 v[22:25], v[192:195], v[216:219], v[22:25]
	v_mfma_f32_16x16x32_bf16 v[10:13], v[184:187], v[240:243], v[10:13]
	v_mfma_f32_16x16x32_bf16 v[6:9], v[192:195], v[240:243], v[6:9]
	s_setprio 0
	s_barrier
	s_add_i32 s12, s12, 2
	s_add_u32 s0, s0, 0x100
	s_addc_u32 s1, s1, 0
	s_add_u32 s10, s10, 0x100
	s_addc_u32 s11, s11, 0
	s_cmp_gt_u32 s12, 13
	s_cbranch_scc0 .LBB0_625
	s_and_b64 vcc, exec, s[24:25]
	s_cbranch_vccz .LBB0_628
	s_barrier
